# v38 + P0 adaLN GEMV rewritten: 48 columns per workgroup on all 256 workgroups (was 64 columns on 192), dwordx3 loads 8 in flight
# speedup vs baseline: 1.0048x; 1.0048x over previous
.LBB0_7:
	s_or_b64 exec, exec, s[2:3]
	s_load_dwordx16 s[52:67], s[0:1], 0x0
	s_load_dwordx16 s[8:23], s[0:1], 0x40
	s_lshr_b32 s91, s6, 6
	s_cmp_lt_i32 s76, 1
	s_cselect_b64 s[0:1], -1, 0
	s_cmp_gt_i32 s77, 0
	s_waitcnt lgkmcnt(0)
	v_writelane_b32 v254, s8, 0
	s_cselect_b64 s[2:3], -1, 0
	s_and_b64 s[0:1], s[0:1], s[2:3]
	v_writelane_b32 v254, s9, 1
	v_writelane_b32 v254, s10, 2
	v_writelane_b32 v254, s11, 3
	v_writelane_b32 v254, s12, 4
	v_writelane_b32 v254, s13, 5
	v_writelane_b32 v254, s14, 6
	v_writelane_b32 v254, s15, 7
	v_writelane_b32 v254, s16, 8
	v_writelane_b32 v254, s17, 9
	v_writelane_b32 v254, s18, 10
	v_writelane_b32 v254, s19, 11
	v_writelane_b32 v254, s20, 12
	v_writelane_b32 v254, s21, 13
	v_writelane_b32 v254, s22, 14
	v_writelane_b32 v254, s23, 15
	s_andn2_b64 vcc, exec, s[0:1]
	s_mov_b64 s[0:1], s[76:77]
	v_writelane_b32 v254, s0, 16
	v_and_b32_e32 v1, 63, v0
	s_nop 0
	v_writelane_b32 v254, s1, 17
	v_writelane_b32 v254, s2, 18
	v_writelane_b32 v254, s3, 19
	s_cbranch_vccnz .LBB0_93
	v_lshlrev_b32_e32 v181, 2, v1
	v_mov_b32_e32 v3, 0
	s_cmpk_lg_i32 s33, 0x100
	s_cbranch_scc1 .Lgv_old
	v_lshlrev_b32_e32 v186, 2, v0
	v_add_u32_e32 v187, 0x1000, v186
	global_load_dword v192, v186, s[64:65]
	global_load_dword v193, v186, s[64:65] offset:2048
	global_load_dword v194, v187, s[64:65]
	global_load_dword v195, v187, s[64:65] offset:2048
	s_mov_b32 s8, s56
	s_mov_b32 s9, s57
	global_load_dword v196, v186, s[8:9]
	global_load_dword v197, v186, s[8:9] offset:2048
	global_load_dword v198, v187, s[8:9]
	global_load_dword v199, v187, s[8:9] offset:2048
	s_add_u32 s8, s8, 0x2000
	s_addc_u32 s9, s9, 0
	global_load_dword v200, v186, s[8:9]
	global_load_dword v201, v186, s[8:9] offset:2048
	global_load_dword v202, v187, s[8:9]
	global_load_dword v203, v187, s[8:9] offset:2048
	s_add_u32 s8, s8, 0x2000
	s_addc_u32 s9, s9, 0
	global_load_dword v204, v186, s[8:9]
	global_load_dword v205, v186, s[8:9] offset:2048
	global_load_dword v206, v187, s[8:9]
	global_load_dword v207, v187, s[8:9] offset:2048
	s_add_u32 s8, s8, 0x2000
	s_addc_u32 s9, s9, 0
	global_load_dword v208, v186, s[8:9]
	global_load_dword v209, v186, s[8:9] offset:2048
	global_load_dword v210, v187, s[8:9]
	global_load_dword v211, v187, s[8:9] offset:2048
	s_add_u32 s8, s8, 0x2000
	s_addc_u32 s9, s9, 0
	global_load_dword v212, v186, s[8:9]
	global_load_dword v213, v186, s[8:9] offset:2048
	global_load_dword v214, v187, s[8:9]
	global_load_dword v215, v187, s[8:9] offset:2048
	s_add_u32 s8, s8, 0x2000
	s_addc_u32 s9, s9, 0
	global_load_dword v216, v186, s[8:9]
	global_load_dword v217, v186, s[8:9] offset:2048
	global_load_dword v218, v187, s[8:9]
	global_load_dword v219, v187, s[8:9] offset:2048
	s_add_u32 s8, s8, 0x2000
	s_addc_u32 s9, s9, 0
	global_load_dword v220, v186, s[8:9]
	global_load_dword v221, v186, s[8:9] offset:2048
	global_load_dword v222, v187, s[8:9]
	global_load_dword v223, v187, s[8:9] offset:2048
	s_add_u32 s8, s8, 0x2000
	s_addc_u32 s9, s9, 0
	global_load_dword v224, v186, s[8:9]
	global_load_dword v225, v186, s[8:9] offset:2048
	global_load_dword v226, v187, s[8:9]
	global_load_dword v227, v187, s[8:9] offset:2048
	v_lshrrev_b32_e32 v5, 4, v1
	v_and_b32_e32 v6, 15, v1
	v_mul_u32_u24_e32 v2, 0xc000, v5
	v_mul_u32_u24_e32 v7, 12, v6
	v_add_u32_e32 v2, v2, v7
	v_readlane_b32 s0, v254, 10
	v_readlane_b32 s1, v254, 11
	s_lshl_b32 s4, s91, 2
	s_mul_i32 s6, s4, 0xc000
	s_mul_i32 s7, s30, 0xc0
	s_add_i32 s6, s6, s7
	s_add_u32 s0, s0, s6
	s_addc_u32 s1, s1, 0
	global_load_dwordx3 v[64:66], v2, s[0:1]
	s_add_u32 s0, s0, 0x180000
	s_addc_u32 s1, s1, 0
	global_load_dwordx3 v[68:70], v2, s[0:1]
	s_add_u32 s0, s0, 0x180000
	s_addc_u32 s1, s1, 0
	global_load_dwordx3 v[72:74], v2, s[0:1]
	s_add_u32 s0, s0, 0x180000
	s_addc_u32 s1, s1, 0
	global_load_dwordx3 v[76:78], v2, s[0:1]
	s_add_u32 s0, s0, 0x180000
	s_addc_u32 s1, s1, 0
	global_load_dwordx3 v[80:82], v2, s[0:1]
	s_add_u32 s0, s0, 0x180000
	s_addc_u32 s1, s1, 0
	global_load_dwordx3 v[84:86], v2, s[0:1]
	s_add_u32 s0, s0, 0x180000
	s_addc_u32 s1, s1, 0
	global_load_dwordx3 v[88:90], v2, s[0:1]
	s_add_u32 s0, s0, 0x180000
	s_addc_u32 s1, s1, 0
	global_load_dwordx3 v[92:94], v2, s[0:1]
	s_add_u32 s0, s0, 0x180000
	s_addc_u32 s1, s1, 0
	v_mul_u32_u24_e32 v188, 48, v0
	v_add_u32_e32 v189, 0x6000, v188
	v_add_u32_e32 v190, 0xc000, v188
	v_add_u32_e32 v191, 0x12000, v188
	v_add_u32_e32 v4, s4, v5
	v_mul_u32_u24_e32 v4, 48, v4
	v_mov_b32_e32 v10, 0
	v_mov_b32_e32 v11, 0
	v_mov_b32_e32 v12, 0
	v_mov_b32_e32 v13, 0
	v_mov_b32_e32 v14, 0
	v_mov_b32_e32 v15, 0
	v_mov_b32_e32 v16, 0
	v_mov_b32_e32 v17, 0
	v_mov_b32_e32 v18, 0
	v_mov_b32_e32 v19, 0
	v_mov_b32_e32 v20, 0
	v_mov_b32_e32 v21, 0
	v_mov_b32_e32 v22, 0
	v_mov_b32_e32 v23, 0
	v_mov_b32_e32 v24, 0
	v_mov_b32_e32 v25, 0
	v_mov_b32_e32 v26, 0
	v_mov_b32_e32 v27, 0
	v_mov_b32_e32 v28, 0
	v_mov_b32_e32 v29, 0
	v_mov_b32_e32 v30, 0
	v_mov_b32_e32 v31, 0
	v_mov_b32_e32 v32, 0
	v_mov_b32_e32 v33, 0
	v_mov_b32_e32 v34, 0
	v_mov_b32_e32 v35, 0
	v_mov_b32_e32 v36, 0
	s_waitcnt vmcnt(43)
	v_mul_f32_e32 v140, 0xbfb8aa3b, v192
	v_exp_f32_e32 v140, v140
	s_nop 1
	v_add_f32_e32 v141, 1.0, v140
	v_div_scale_f32 v142, s[20:21], v141, v141, v192
	v_div_scale_f32 v143, vcc, v192, v141, v192
	v_rcp_f32_e32 v144, v142
	s_nop 1
	v_fma_f32 v145, -v142, v144, 1.0
	v_fmac_f32_e32 v144, v145, v144
	v_mul_f32_e32 v135, v143, v144
	v_fma_f32 v145, -v142, v135, v143
	v_fmac_f32_e32 v135, v145, v144
	v_fma_f32 v145, -v142, v135, v143
	s_nop 1
	v_div_fmas_f32 v145, v145, v144, v135
	v_div_fixup_f32 v135, v145, v141, v192
	ds_write_b32 v188, v135
	s_waitcnt vmcnt(42)
	v_mul_f32_e32 v140, 0xbfb8aa3b, v193
	v_exp_f32_e32 v140, v140
	s_nop 1
	v_add_f32_e32 v141, 1.0, v140
	v_div_scale_f32 v142, s[20:21], v141, v141, v193
	v_div_scale_f32 v143, vcc, v193, v141, v193
	v_rcp_f32_e32 v144, v142
	s_nop 1
	v_fma_f32 v145, -v142, v144, 1.0
	v_fmac_f32_e32 v144, v145, v144
	v_mul_f32_e32 v135, v143, v144
	v_fma_f32 v145, -v142, v135, v143
	v_fmac_f32_e32 v135, v145, v144
	v_fma_f32 v145, -v142, v135, v143
	s_nop 1
	v_div_fmas_f32 v145, v145, v144, v135
	v_div_fixup_f32 v135, v145, v141, v193
	ds_write_b32 v189, v135
	s_waitcnt vmcnt(41)
	v_mul_f32_e32 v140, 0xbfb8aa3b, v194
	v_exp_f32_e32 v140, v140
	s_nop 1
	v_add_f32_e32 v141, 1.0, v140
	v_div_scale_f32 v142, s[20:21], v141, v141, v194
	v_div_scale_f32 v143, vcc, v194, v141, v194
	v_rcp_f32_e32 v144, v142
	s_nop 1
	v_fma_f32 v145, -v142, v144, 1.0
	v_fmac_f32_e32 v144, v145, v144
	v_mul_f32_e32 v135, v143, v144
	v_fma_f32 v145, -v142, v135, v143
	v_fmac_f32_e32 v135, v145, v144
	v_fma_f32 v145, -v142, v135, v143
	s_nop 1
	v_div_fmas_f32 v145, v145, v144, v135
	v_div_fixup_f32 v135, v145, v141, v194
	ds_write_b32 v190, v135
	s_waitcnt vmcnt(40)
	v_mul_f32_e32 v140, 0xbfb8aa3b, v195
	v_exp_f32_e32 v140, v140
	s_nop 1
	v_add_f32_e32 v141, 1.0, v140
	v_div_scale_f32 v142, s[20:21], v141, v141, v195
	v_div_scale_f32 v143, vcc, v195, v141, v195
	v_rcp_f32_e32 v144, v142
	s_nop 1
	v_fma_f32 v145, -v142, v144, 1.0
	v_fmac_f32_e32 v144, v145, v144
	v_mul_f32_e32 v135, v143, v144
	v_fma_f32 v145, -v142, v135, v143
	v_fmac_f32_e32 v135, v145, v144
	v_fma_f32 v145, -v142, v135, v143
	s_nop 1
	v_div_fmas_f32 v145, v145, v144, v135
	v_div_fixup_f32 v135, v145, v141, v195
	ds_write_b32 v191, v135
	s_waitcnt vmcnt(39)
	v_mul_f32_e32 v140, 0xbfb8aa3b, v196
	v_exp_f32_e32 v140, v140
	s_nop 1
	v_add_f32_e32 v141, 1.0, v140
	v_div_scale_f32 v142, s[20:21], v141, v141, v196
	v_div_scale_f32 v143, vcc, v196, v141, v196
	v_rcp_f32_e32 v144, v142
	s_nop 1
	v_fma_f32 v145, -v142, v144, 1.0
	v_fmac_f32_e32 v144, v145, v144
	v_mul_f32_e32 v135, v143, v144
	v_fma_f32 v145, -v142, v135, v143
	v_fmac_f32_e32 v135, v145, v144
	v_fma_f32 v145, -v142, v135, v143
	s_nop 1
	v_div_fmas_f32 v145, v145, v144, v135
	v_div_fixup_f32 v135, v145, v141, v196
	ds_write_b32 v188, v135 offset:4
	s_waitcnt vmcnt(38)
	v_mul_f32_e32 v140, 0xbfb8aa3b, v197
	v_exp_f32_e32 v140, v140
	s_nop 1
	v_add_f32_e32 v141, 1.0, v140
	v_div_scale_f32 v142, s[20:21], v141, v141, v197
	v_div_scale_f32 v143, vcc, v197, v141, v197
	v_rcp_f32_e32 v144, v142
	s_nop 1
	v_fma_f32 v145, -v142, v144, 1.0
	v_fmac_f32_e32 v144, v145, v144
	v_mul_f32_e32 v135, v143, v144
	v_fma_f32 v145, -v142, v135, v143
	v_fmac_f32_e32 v135, v145, v144
	v_fma_f32 v145, -v142, v135, v143
	s_nop 1
	v_div_fmas_f32 v145, v145, v144, v135
	v_div_fixup_f32 v135, v145, v141, v197
	ds_write_b32 v189, v135 offset:4
	s_waitcnt vmcnt(37)
	v_mul_f32_e32 v140, 0xbfb8aa3b, v198
	v_exp_f32_e32 v140, v140
	s_nop 1
	v_add_f32_e32 v141, 1.0, v140
	v_div_scale_f32 v142, s[20:21], v141, v141, v198
	v_div_scale_f32 v143, vcc, v198, v141, v198
	v_rcp_f32_e32 v144, v142
	s_nop 1
	v_fma_f32 v145, -v142, v144, 1.0
	v_fmac_f32_e32 v144, v145, v144
	v_mul_f32_e32 v135, v143, v144
	v_fma_f32 v145, -v142, v135, v143
	v_fmac_f32_e32 v135, v145, v144
	v_fma_f32 v145, -v142, v135, v143
	s_nop 1
	v_div_fmas_f32 v145, v145, v144, v135
	v_div_fixup_f32 v135, v145, v141, v198
	ds_write_b32 v190, v135 offset:4
	s_waitcnt vmcnt(36)
	v_mul_f32_e32 v140, 0xbfb8aa3b, v199
	v_exp_f32_e32 v140, v140
	s_nop 1
	v_add_f32_e32 v141, 1.0, v140
	v_div_scale_f32 v142, s[20:21], v141, v141, v199
	v_div_scale_f32 v143, vcc, v199, v141, v199
	v_rcp_f32_e32 v144, v142
	s_nop 1
	v_fma_f32 v145, -v142, v144, 1.0
	v_fmac_f32_e32 v144, v145, v144
	v_mul_f32_e32 v135, v143, v144
	v_fma_f32 v145, -v142, v135, v143
	v_fmac_f32_e32 v135, v145, v144
	v_fma_f32 v145, -v142, v135, v143
	s_nop 1
	v_div_fmas_f32 v145, v145, v144, v135
	v_div_fixup_f32 v135, v145, v141, v199
	ds_write_b32 v191, v135 offset:4
	s_waitcnt vmcnt(35)
	v_mul_f32_e32 v140, 0xbfb8aa3b, v200
	v_exp_f32_e32 v140, v140
	s_nop 1
	v_add_f32_e32 v141, 1.0, v140
	v_div_scale_f32 v142, s[20:21], v141, v141, v200
	v_div_scale_f32 v143, vcc, v200, v141, v200
	v_rcp_f32_e32 v144, v142
	s_nop 1
	v_fma_f32 v145, -v142, v144, 1.0
	v_fmac_f32_e32 v144, v145, v144
	v_mul_f32_e32 v135, v143, v144
	v_fma_f32 v145, -v142, v135, v143
	v_fmac_f32_e32 v135, v145, v144
	v_fma_f32 v145, -v142, v135, v143
	s_nop 1
	v_div_fmas_f32 v145, v145, v144, v135
	v_div_fixup_f32 v135, v145, v141, v200
	ds_write_b32 v188, v135 offset:8
	s_waitcnt vmcnt(34)
	v_mul_f32_e32 v140, 0xbfb8aa3b, v201
	v_exp_f32_e32 v140, v140
	s_nop 1
	v_add_f32_e32 v141, 1.0, v140
	v_div_scale_f32 v142, s[20:21], v141, v141, v201
	v_div_scale_f32 v143, vcc, v201, v141, v201
	v_rcp_f32_e32 v144, v142
	s_nop 1
	v_fma_f32 v145, -v142, v144, 1.0
	v_fmac_f32_e32 v144, v145, v144
	v_mul_f32_e32 v135, v143, v144
	v_fma_f32 v145, -v142, v135, v143
	v_fmac_f32_e32 v135, v145, v144
	v_fma_f32 v145, -v142, v135, v143
	s_nop 1
	v_div_fmas_f32 v145, v145, v144, v135
	v_div_fixup_f32 v135, v145, v141, v201
	ds_write_b32 v189, v135 offset:8
	s_waitcnt vmcnt(33)
	v_mul_f32_e32 v140, 0xbfb8aa3b, v202
	v_exp_f32_e32 v140, v140
	s_nop 1
	v_add_f32_e32 v141, 1.0, v140
	v_div_scale_f32 v142, s[20:21], v141, v141, v202
	v_div_scale_f32 v143, vcc, v202, v141, v202
	v_rcp_f32_e32 v144, v142
	s_nop 1
	v_fma_f32 v145, -v142, v144, 1.0
	v_fmac_f32_e32 v144, v145, v144
	v_mul_f32_e32 v135, v143, v144
	v_fma_f32 v145, -v142, v135, v143
	v_fmac_f32_e32 v135, v145, v144
	v_fma_f32 v145, -v142, v135, v143
	s_nop 1
	v_div_fmas_f32 v145, v145, v144, v135
	v_div_fixup_f32 v135, v145, v141, v202
	ds_write_b32 v190, v135 offset:8
	s_waitcnt vmcnt(32)
	v_mul_f32_e32 v140, 0xbfb8aa3b, v203
	v_exp_f32_e32 v140, v140
	s_nop 1
	v_add_f32_e32 v141, 1.0, v140
	v_div_scale_f32 v142, s[20:21], v141, v141, v203
	v_div_scale_f32 v143, vcc, v203, v141, v203
	v_rcp_f32_e32 v144, v142
	s_nop 1
	v_fma_f32 v145, -v142, v144, 1.0
	v_fmac_f32_e32 v144, v145, v144
	v_mul_f32_e32 v135, v143, v144
	v_fma_f32 v145, -v142, v135, v143
	v_fmac_f32_e32 v135, v145, v144
	v_fma_f32 v145, -v142, v135, v143
	s_nop 1
	v_div_fmas_f32 v145, v145, v144, v135
	v_div_fixup_f32 v135, v145, v141, v203
	ds_write_b32 v191, v135 offset:8
	s_waitcnt vmcnt(31)
	v_mul_f32_e32 v140, 0xbfb8aa3b, v204
	v_exp_f32_e32 v140, v140
	s_nop 1
	v_add_f32_e32 v141, 1.0, v140
	v_div_scale_f32 v142, s[20:21], v141, v141, v204
	v_div_scale_f32 v143, vcc, v204, v141, v204
	v_rcp_f32_e32 v144, v142
	s_nop 1
	v_fma_f32 v145, -v142, v144, 1.0
	v_fmac_f32_e32 v144, v145, v144
	v_mul_f32_e32 v135, v143, v144
	v_fma_f32 v145, -v142, v135, v143
	v_fmac_f32_e32 v135, v145, v144
	v_fma_f32 v145, -v142, v135, v143
	s_nop 1
	v_div_fmas_f32 v145, v145, v144, v135
	v_div_fixup_f32 v135, v145, v141, v204
	ds_write_b32 v188, v135 offset:12
	s_waitcnt vmcnt(30)
	v_mul_f32_e32 v140, 0xbfb8aa3b, v205
	v_exp_f32_e32 v140, v140
	s_nop 1
	v_add_f32_e32 v141, 1.0, v140
	v_div_scale_f32 v142, s[20:21], v141, v141, v205
	v_div_scale_f32 v143, vcc, v205, v141, v205
	v_rcp_f32_e32 v144, v142
	s_nop 1
	v_fma_f32 v145, -v142, v144, 1.0
	v_fmac_f32_e32 v144, v145, v144
	v_mul_f32_e32 v135, v143, v144
	v_fma_f32 v145, -v142, v135, v143
	v_fmac_f32_e32 v135, v145, v144
	v_fma_f32 v145, -v142, v135, v143
	s_nop 1
	v_div_fmas_f32 v145, v145, v144, v135
	v_div_fixup_f32 v135, v145, v141, v205
	ds_write_b32 v189, v135 offset:12
	s_waitcnt vmcnt(29)
	v_mul_f32_e32 v140, 0xbfb8aa3b, v206
	v_exp_f32_e32 v140, v140
	s_nop 1
	v_add_f32_e32 v141, 1.0, v140
	v_div_scale_f32 v142, s[20:21], v141, v141, v206
	v_div_scale_f32 v143, vcc, v206, v141, v206
	v_rcp_f32_e32 v144, v142
	s_nop 1
	v_fma_f32 v145, -v142, v144, 1.0
	v_fmac_f32_e32 v144, v145, v144
	v_mul_f32_e32 v135, v143, v144
	v_fma_f32 v145, -v142, v135, v143
	v_fmac_f32_e32 v135, v145, v144
	v_fma_f32 v145, -v142, v135, v143
	s_nop 1
	v_div_fmas_f32 v145, v145, v144, v135
	v_div_fixup_f32 v135, v145, v141, v206
	ds_write_b32 v190, v135 offset:12
	s_waitcnt vmcnt(28)
	v_mul_f32_e32 v140, 0xbfb8aa3b, v207
	v_exp_f32_e32 v140, v140
	s_nop 1
	v_add_f32_e32 v141, 1.0, v140
	v_div_scale_f32 v142, s[20:21], v141, v141, v207
	v_div_scale_f32 v143, vcc, v207, v141, v207
	v_rcp_f32_e32 v144, v142
	s_nop 1
	v_fma_f32 v145, -v142, v144, 1.0
	v_fmac_f32_e32 v144, v145, v144
	v_mul_f32_e32 v135, v143, v144
	v_fma_f32 v145, -v142, v135, v143
	v_fmac_f32_e32 v135, v145, v144
	v_fma_f32 v145, -v142, v135, v143
	s_nop 1
	v_div_fmas_f32 v145, v145, v144, v135
	v_div_fixup_f32 v135, v145, v141, v207
	ds_write_b32 v191, v135 offset:12
	s_waitcnt vmcnt(27)
	v_mul_f32_e32 v140, 0xbfb8aa3b, v208
	v_exp_f32_e32 v140, v140
	s_nop 1
	v_add_f32_e32 v141, 1.0, v140
	v_div_scale_f32 v142, s[20:21], v141, v141, v208
	v_div_scale_f32 v143, vcc, v208, v141, v208
	v_rcp_f32_e32 v144, v142
	s_nop 1
	v_fma_f32 v145, -v142, v144, 1.0
	v_fmac_f32_e32 v144, v145, v144
	v_mul_f32_e32 v135, v143, v144
	v_fma_f32 v145, -v142, v135, v143
	v_fmac_f32_e32 v135, v145, v144
	v_fma_f32 v145, -v142, v135, v143
	s_nop 1
	v_div_fmas_f32 v145, v145, v144, v135
	v_div_fixup_f32 v135, v145, v141, v208
	ds_write_b32 v188, v135 offset:16
	s_waitcnt vmcnt(26)
	v_mul_f32_e32 v140, 0xbfb8aa3b, v209
	v_exp_f32_e32 v140, v140
	s_nop 1
	v_add_f32_e32 v141, 1.0, v140
	v_div_scale_f32 v142, s[20:21], v141, v141, v209
	v_div_scale_f32 v143, vcc, v209, v141, v209
	v_rcp_f32_e32 v144, v142
	s_nop 1
	v_fma_f32 v145, -v142, v144, 1.0
	v_fmac_f32_e32 v144, v145, v144
	v_mul_f32_e32 v135, v143, v144
	v_fma_f32 v145, -v142, v135, v143
	v_fmac_f32_e32 v135, v145, v144
	v_fma_f32 v145, -v142, v135, v143
	s_nop 1
	v_div_fmas_f32 v145, v145, v144, v135
	v_div_fixup_f32 v135, v145, v141, v209
	ds_write_b32 v189, v135 offset:16
	s_waitcnt vmcnt(25)
	v_mul_f32_e32 v140, 0xbfb8aa3b, v210
	v_exp_f32_e32 v140, v140
	s_nop 1
	v_add_f32_e32 v141, 1.0, v140
	v_div_scale_f32 v142, s[20:21], v141, v141, v210
	v_div_scale_f32 v143, vcc, v210, v141, v210
	v_rcp_f32_e32 v144, v142
	s_nop 1
	v_fma_f32 v145, -v142, v144, 1.0
	v_fmac_f32_e32 v144, v145, v144
	v_mul_f32_e32 v135, v143, v144
	v_fma_f32 v145, -v142, v135, v143
	v_fmac_f32_e32 v135, v145, v144
	v_fma_f32 v145, -v142, v135, v143
	s_nop 1
	v_div_fmas_f32 v145, v145, v144, v135
	v_div_fixup_f32 v135, v145, v141, v210
	ds_write_b32 v190, v135 offset:16
	s_waitcnt vmcnt(24)
	v_mul_f32_e32 v140, 0xbfb8aa3b, v211
	v_exp_f32_e32 v140, v140
	s_nop 1
	v_add_f32_e32 v141, 1.0, v140
	v_div_scale_f32 v142, s[20:21], v141, v141, v211
	v_div_scale_f32 v143, vcc, v211, v141, v211
	v_rcp_f32_e32 v144, v142
	s_nop 1
	v_fma_f32 v145, -v142, v144, 1.0
	v_fmac_f32_e32 v144, v145, v144
	v_mul_f32_e32 v135, v143, v144
	v_fma_f32 v145, -v142, v135, v143
	v_fmac_f32_e32 v135, v145, v144
	v_fma_f32 v145, -v142, v135, v143
	s_nop 1
	v_div_fmas_f32 v145, v145, v144, v135
	v_div_fixup_f32 v135, v145, v141, v211
	ds_write_b32 v191, v135 offset:16
	s_waitcnt vmcnt(23)
	v_mul_f32_e32 v140, 0xbfb8aa3b, v212
	v_exp_f32_e32 v140, v140
	s_nop 1
	v_add_f32_e32 v141, 1.0, v140
	v_div_scale_f32 v142, s[20:21], v141, v141, v212
	v_div_scale_f32 v143, vcc, v212, v141, v212
	v_rcp_f32_e32 v144, v142
	s_nop 1
	v_fma_f32 v145, -v142, v144, 1.0
	v_fmac_f32_e32 v144, v145, v144
	v_mul_f32_e32 v135, v143, v144
	v_fma_f32 v145, -v142, v135, v143
	v_fmac_f32_e32 v135, v145, v144
	v_fma_f32 v145, -v142, v135, v143
	s_nop 1
	v_div_fmas_f32 v145, v145, v144, v135
	v_div_fixup_f32 v135, v145, v141, v212
	ds_write_b32 v188, v135 offset:20
	s_waitcnt vmcnt(22)
	v_mul_f32_e32 v140, 0xbfb8aa3b, v213
	v_exp_f32_e32 v140, v140
	s_nop 1
	v_add_f32_e32 v141, 1.0, v140
	v_div_scale_f32 v142, s[20:21], v141, v141, v213
	v_div_scale_f32 v143, vcc, v213, v141, v213
	v_rcp_f32_e32 v144, v142
	s_nop 1
	v_fma_f32 v145, -v142, v144, 1.0
	v_fmac_f32_e32 v144, v145, v144
	v_mul_f32_e32 v135, v143, v144
	v_fma_f32 v145, -v142, v135, v143
	v_fmac_f32_e32 v135, v145, v144
	v_fma_f32 v145, -v142, v135, v143
	s_nop 1
	v_div_fmas_f32 v145, v145, v144, v135
	v_div_fixup_f32 v135, v145, v141, v213
	ds_write_b32 v189, v135 offset:20
	s_waitcnt vmcnt(21)
	v_mul_f32_e32 v140, 0xbfb8aa3b, v214
	v_exp_f32_e32 v140, v140
	s_nop 1
	v_add_f32_e32 v141, 1.0, v140
	v_div_scale_f32 v142, s[20:21], v141, v141, v214
	v_div_scale_f32 v143, vcc, v214, v141, v214
	v_rcp_f32_e32 v144, v142
	s_nop 1
	v_fma_f32 v145, -v142, v144, 1.0
	v_fmac_f32_e32 v144, v145, v144
	v_mul_f32_e32 v135, v143, v144
	v_fma_f32 v145, -v142, v135, v143
	v_fmac_f32_e32 v135, v145, v144
	v_fma_f32 v145, -v142, v135, v143
	s_nop 1
	v_div_fmas_f32 v145, v145, v144, v135
	v_div_fixup_f32 v135, v145, v141, v214
	ds_write_b32 v190, v135 offset:20
	s_waitcnt vmcnt(20)
	v_mul_f32_e32 v140, 0xbfb8aa3b, v215
	v_exp_f32_e32 v140, v140
	s_nop 1
	v_add_f32_e32 v141, 1.0, v140
	v_div_scale_f32 v142, s[20:21], v141, v141, v215
	v_div_scale_f32 v143, vcc, v215, v141, v215
	v_rcp_f32_e32 v144, v142
	s_nop 1
	v_fma_f32 v145, -v142, v144, 1.0
	v_fmac_f32_e32 v144, v145, v144
	v_mul_f32_e32 v135, v143, v144
	v_fma_f32 v145, -v142, v135, v143
	v_fmac_f32_e32 v135, v145, v144
	v_fma_f32 v145, -v142, v135, v143
	s_nop 1
	v_div_fmas_f32 v145, v145, v144, v135
	v_div_fixup_f32 v135, v145, v141, v215
	ds_write_b32 v191, v135 offset:20
	s_waitcnt vmcnt(19)
	v_mul_f32_e32 v140, 0xbfb8aa3b, v216
	v_exp_f32_e32 v140, v140
	s_nop 1
	v_add_f32_e32 v141, 1.0, v140
	v_div_scale_f32 v142, s[20:21], v141, v141, v216
	v_div_scale_f32 v143, vcc, v216, v141, v216
	v_rcp_f32_e32 v144, v142
	s_nop 1
	v_fma_f32 v145, -v142, v144, 1.0
	v_fmac_f32_e32 v144, v145, v144
	v_mul_f32_e32 v135, v143, v144
	v_fma_f32 v145, -v142, v135, v143
	v_fmac_f32_e32 v135, v145, v144
	v_fma_f32 v145, -v142, v135, v143
	s_nop 1
	v_div_fmas_f32 v145, v145, v144, v135
	v_div_fixup_f32 v135, v145, v141, v216
	ds_write_b32 v188, v135 offset:24
	s_waitcnt vmcnt(18)
	v_mul_f32_e32 v140, 0xbfb8aa3b, v217
	v_exp_f32_e32 v140, v140
	s_nop 1
	v_add_f32_e32 v141, 1.0, v140
	v_div_scale_f32 v142, s[20:21], v141, v141, v217
	v_div_scale_f32 v143, vcc, v217, v141, v217
	v_rcp_f32_e32 v144, v142
	s_nop 1
	v_fma_f32 v145, -v142, v144, 1.0
	v_fmac_f32_e32 v144, v145, v144
	v_mul_f32_e32 v135, v143, v144
	v_fma_f32 v145, -v142, v135, v143
	v_fmac_f32_e32 v135, v145, v144
	v_fma_f32 v145, -v142, v135, v143
	s_nop 1
	v_div_fmas_f32 v145, v145, v144, v135
	v_div_fixup_f32 v135, v145, v141, v217
	ds_write_b32 v189, v135 offset:24
	s_waitcnt vmcnt(17)
	v_mul_f32_e32 v140, 0xbfb8aa3b, v218
	v_exp_f32_e32 v140, v140
	s_nop 1
	v_add_f32_e32 v141, 1.0, v140
	v_div_scale_f32 v142, s[20:21], v141, v141, v218
	v_div_scale_f32 v143, vcc, v218, v141, v218
	v_rcp_f32_e32 v144, v142
	s_nop 1
	v_fma_f32 v145, -v142, v144, 1.0
	v_fmac_f32_e32 v144, v145, v144
	v_mul_f32_e32 v135, v143, v144
	v_fma_f32 v145, -v142, v135, v143
	v_fmac_f32_e32 v135, v145, v144
	v_fma_f32 v145, -v142, v135, v143
	s_nop 1
	v_div_fmas_f32 v145, v145, v144, v135
	v_div_fixup_f32 v135, v145, v141, v218
	ds_write_b32 v190, v135 offset:24
	s_waitcnt vmcnt(16)
	v_mul_f32_e32 v140, 0xbfb8aa3b, v219
	v_exp_f32_e32 v140, v140
	s_nop 1
	v_add_f32_e32 v141, 1.0, v140
	v_div_scale_f32 v142, s[20:21], v141, v141, v219
	v_div_scale_f32 v143, vcc, v219, v141, v219
	v_rcp_f32_e32 v144, v142
	s_nop 1
	v_fma_f32 v145, -v142, v144, 1.0
	v_fmac_f32_e32 v144, v145, v144
	v_mul_f32_e32 v135, v143, v144
	v_fma_f32 v145, -v142, v135, v143
	v_fmac_f32_e32 v135, v145, v144
	v_fma_f32 v145, -v142, v135, v143
	s_nop 1
	v_div_fmas_f32 v145, v145, v144, v135
	v_div_fixup_f32 v135, v145, v141, v219
	ds_write_b32 v191, v135 offset:24
	s_waitcnt vmcnt(15)
	v_mul_f32_e32 v140, 0xbfb8aa3b, v220
	v_exp_f32_e32 v140, v140
	s_nop 1
	v_add_f32_e32 v141, 1.0, v140
	v_div_scale_f32 v142, s[20:21], v141, v141, v220
	v_div_scale_f32 v143, vcc, v220, v141, v220
	v_rcp_f32_e32 v144, v142
	s_nop 1
	v_fma_f32 v145, -v142, v144, 1.0
	v_fmac_f32_e32 v144, v145, v144
	v_mul_f32_e32 v135, v143, v144
	v_fma_f32 v145, -v142, v135, v143
	v_fmac_f32_e32 v135, v145, v144
	v_fma_f32 v145, -v142, v135, v143
	s_nop 1
	v_div_fmas_f32 v145, v145, v144, v135
	v_div_fixup_f32 v135, v145, v141, v220
	ds_write_b32 v188, v135 offset:28
	s_waitcnt vmcnt(14)
	v_mul_f32_e32 v140, 0xbfb8aa3b, v221
	v_exp_f32_e32 v140, v140
	s_nop 1
	v_add_f32_e32 v141, 1.0, v140
	v_div_scale_f32 v142, s[20:21], v141, v141, v221
	v_div_scale_f32 v143, vcc, v221, v141, v221
	v_rcp_f32_e32 v144, v142
	s_nop 1
	v_fma_f32 v145, -v142, v144, 1.0
	v_fmac_f32_e32 v144, v145, v144
	v_mul_f32_e32 v135, v143, v144
	v_fma_f32 v145, -v142, v135, v143
	v_fmac_f32_e32 v135, v145, v144
	v_fma_f32 v145, -v142, v135, v143
	s_nop 1
	v_div_fmas_f32 v145, v145, v144, v135
	v_div_fixup_f32 v135, v145, v141, v221
	ds_write_b32 v189, v135 offset:28
	s_waitcnt vmcnt(13)
	v_mul_f32_e32 v140, 0xbfb8aa3b, v222
	v_exp_f32_e32 v140, v140
	s_nop 1
	v_add_f32_e32 v141, 1.0, v140
	v_div_scale_f32 v142, s[20:21], v141, v141, v222
	v_div_scale_f32 v143, vcc, v222, v141, v222
	v_rcp_f32_e32 v144, v142
	s_nop 1
	v_fma_f32 v145, -v142, v144, 1.0
	v_fmac_f32_e32 v144, v145, v144
	v_mul_f32_e32 v135, v143, v144
	v_fma_f32 v145, -v142, v135, v143
	v_fmac_f32_e32 v135, v145, v144
	v_fma_f32 v145, -v142, v135, v143
	s_nop 1
	v_div_fmas_f32 v145, v145, v144, v135
	v_div_fixup_f32 v135, v145, v141, v222
	ds_write_b32 v190, v135 offset:28
	s_waitcnt vmcnt(12)
	v_mul_f32_e32 v140, 0xbfb8aa3b, v223
	v_exp_f32_e32 v140, v140
	s_nop 1
	v_add_f32_e32 v141, 1.0, v140
	v_div_scale_f32 v142, s[20:21], v141, v141, v223
	v_div_scale_f32 v143, vcc, v223, v141, v223
	v_rcp_f32_e32 v144, v142
	s_nop 1
	v_fma_f32 v145, -v142, v144, 1.0
	v_fmac_f32_e32 v144, v145, v144
	v_mul_f32_e32 v135, v143, v144
	v_fma_f32 v145, -v142, v135, v143
	v_fmac_f32_e32 v135, v145, v144
	v_fma_f32 v145, -v142, v135, v143
	s_nop 1
	v_div_fmas_f32 v145, v145, v144, v135
	v_div_fixup_f32 v135, v145, v141, v223
	ds_write_b32 v191, v135 offset:28
	s_waitcnt vmcnt(11)
	v_mul_f32_e32 v140, 0xbfb8aa3b, v224
	v_exp_f32_e32 v140, v140
	s_nop 1
	v_add_f32_e32 v141, 1.0, v140
	v_div_scale_f32 v142, s[20:21], v141, v141, v224
	v_div_scale_f32 v143, vcc, v224, v141, v224
	v_rcp_f32_e32 v144, v142
	s_nop 1
	v_fma_f32 v145, -v142, v144, 1.0
	v_fmac_f32_e32 v144, v145, v144
	v_mul_f32_e32 v135, v143, v144
	v_fma_f32 v145, -v142, v135, v143
	v_fmac_f32_e32 v135, v145, v144
	v_fma_f32 v145, -v142, v135, v143
	s_nop 1
	v_div_fmas_f32 v145, v145, v144, v135
	v_div_fixup_f32 v135, v145, v141, v224
	ds_write_b32 v188, v135 offset:32
	s_waitcnt vmcnt(10)
	v_mul_f32_e32 v140, 0xbfb8aa3b, v225
	v_exp_f32_e32 v140, v140
	s_nop 1
	v_add_f32_e32 v141, 1.0, v140
	v_div_scale_f32 v142, s[20:21], v141, v141, v225
	v_div_scale_f32 v143, vcc, v225, v141, v225
	v_rcp_f32_e32 v144, v142
	s_nop 1
	v_fma_f32 v145, -v142, v144, 1.0
	v_fmac_f32_e32 v144, v145, v144
	v_mul_f32_e32 v135, v143, v144
	v_fma_f32 v145, -v142, v135, v143
	v_fmac_f32_e32 v135, v145, v144
	v_fma_f32 v145, -v142, v135, v143
	s_nop 1
	v_div_fmas_f32 v145, v145, v144, v135
	v_div_fixup_f32 v135, v145, v141, v225
	ds_write_b32 v189, v135 offset:32
	s_waitcnt vmcnt(9)
	v_mul_f32_e32 v140, 0xbfb8aa3b, v226
	v_exp_f32_e32 v140, v140
	s_nop 1
	v_add_f32_e32 v141, 1.0, v140
	v_div_scale_f32 v142, s[20:21], v141, v141, v226
	v_div_scale_f32 v143, vcc, v226, v141, v226
	v_rcp_f32_e32 v144, v142
	s_nop 1
	v_fma_f32 v145, -v142, v144, 1.0
	v_fmac_f32_e32 v144, v145, v144
	v_mul_f32_e32 v135, v143, v144
	v_fma_f32 v145, -v142, v135, v143
	v_fmac_f32_e32 v135, v145, v144
	v_fma_f32 v145, -v142, v135, v143
	s_nop 1
	v_div_fmas_f32 v145, v145, v144, v135
	v_div_fixup_f32 v135, v145, v141, v226
	ds_write_b32 v190, v135 offset:32
	s_waitcnt vmcnt(8)
	v_mul_f32_e32 v140, 0xbfb8aa3b, v227
	v_exp_f32_e32 v140, v140
	s_nop 1
	v_add_f32_e32 v141, 1.0, v140
	v_div_scale_f32 v142, s[20:21], v141, v141, v227
	v_div_scale_f32 v143, vcc, v227, v141, v227
	v_rcp_f32_e32 v144, v142
	s_nop 1
	v_fma_f32 v145, -v142, v144, 1.0
	v_fmac_f32_e32 v144, v145, v144
	v_mul_f32_e32 v135, v143, v144
	v_fma_f32 v145, -v142, v135, v143
	v_fmac_f32_e32 v135, v145, v144
	v_fma_f32 v145, -v142, v135, v143
	s_nop 1
	v_div_fmas_f32 v145, v145, v144, v135
	v_div_fixup_f32 v135, v145, v141, v227
	ds_write_b32 v191, v135 offset:32
	s_waitcnt lgkmcnt(0)
	s_barrier
	ds_read_b128 v[40:43], v4 offset:0
	ds_read_b128 v[44:47], v4 offset:16
	ds_read_b32 v48, v4 offset:32
	ds_read_b128 v[52:55], v4 offset:1536
	ds_read_b128 v[56:59], v4 offset:1552
	ds_read_b32 v60, v4 offset:1568
	s_mov_b32 s16, 0
.Lgv_loop:
	s_cmp_eq_u32 s16, 7
	s_cselect_b64 s[14:15], 0, -1
	s_waitcnt vmcnt(7)
	s_waitcnt lgkmcnt(3)
	v_pk_fma_f32 v[10:11], v[64:65], v[40:41], v[10:11] op_sel_hi:[1,0,1]
	v_pk_fma_f32 v[12:13], v[64:65], v[40:41], v[12:13] op_sel:[0,1,0]
	v_pk_fma_f32 v[14:15], v[64:65], v[42:43], v[14:15] op_sel_hi:[1,0,1]
	v_pk_fma_f32 v[16:17], v[64:65], v[42:43], v[16:17] op_sel:[0,1,0]
	v_pk_fma_f32 v[18:19], v[64:65], v[44:45], v[18:19] op_sel_hi:[1,0,1]
	v_pk_fma_f32 v[20:21], v[64:65], v[44:45], v[20:21] op_sel:[0,1,0]
	v_pk_fma_f32 v[22:23], v[64:65], v[46:47], v[22:23] op_sel_hi:[1,0,1]
	v_pk_fma_f32 v[24:25], v[64:65], v[46:47], v[24:25] op_sel:[0,1,0]
	v_pk_fma_f32 v[26:27], v[64:65], v[48:49], v[26:27] op_sel_hi:[1,0,1]
	v_pk_fma_f32 v[28:29], v[66:67], v[40:41], v[28:29] op_sel_hi:[0,1,1]
	v_pk_fma_f32 v[30:31], v[66:67], v[42:43], v[30:31] op_sel_hi:[0,1,1]
	v_pk_fma_f32 v[32:33], v[66:67], v[44:45], v[32:33] op_sel_hi:[0,1,1]
	v_pk_fma_f32 v[34:35], v[66:67], v[46:47], v[34:35] op_sel_hi:[0,1,1]
	v_fmac_f32_e32 v36, v66, v48
	s_mov_b64 exec, s[14:15]
	global_load_dwordx3 v[64:66], v2, s[0:1]
	s_mov_b64 exec, -1
	s_add_u32 s0, s0, 0x180000
	s_addc_u32 s1, s1, 0
	ds_read_b128 v[40:43], v4 offset:3072
	ds_read_b128 v[44:47], v4 offset:3088
	ds_read_b32 v48, v4 offset:3104
	s_waitcnt vmcnt(7)
	s_waitcnt lgkmcnt(3)
	v_pk_fma_f32 v[10:11], v[68:69], v[52:53], v[10:11] op_sel_hi:[1,0,1]
	v_pk_fma_f32 v[12:13], v[68:69], v[52:53], v[12:13] op_sel:[0,1,0]
	v_pk_fma_f32 v[14:15], v[68:69], v[54:55], v[14:15] op_sel_hi:[1,0,1]
	v_pk_fma_f32 v[16:17], v[68:69], v[54:55], v[16:17] op_sel:[0,1,0]
	v_pk_fma_f32 v[18:19], v[68:69], v[56:57], v[18:19] op_sel_hi:[1,0,1]
	v_pk_fma_f32 v[20:21], v[68:69], v[56:57], v[20:21] op_sel:[0,1,0]
	v_pk_fma_f32 v[22:23], v[68:69], v[58:59], v[22:23] op_sel_hi:[1,0,1]
	v_pk_fma_f32 v[24:25], v[68:69], v[58:59], v[24:25] op_sel:[0,1,0]
	v_pk_fma_f32 v[26:27], v[68:69], v[60:61], v[26:27] op_sel_hi:[1,0,1]
	v_pk_fma_f32 v[28:29], v[70:71], v[52:53], v[28:29] op_sel_hi:[0,1,1]
	v_pk_fma_f32 v[30:31], v[70:71], v[54:55], v[30:31] op_sel_hi:[0,1,1]
	v_pk_fma_f32 v[32:33], v[70:71], v[56:57], v[32:33] op_sel_hi:[0,1,1]
	v_pk_fma_f32 v[34:35], v[70:71], v[58:59], v[34:35] op_sel_hi:[0,1,1]
	v_fmac_f32_e32 v36, v70, v60
	s_mov_b64 exec, s[14:15]
	global_load_dwordx3 v[68:70], v2, s[0:1]
	s_mov_b64 exec, -1
	s_add_u32 s0, s0, 0x180000
	s_addc_u32 s1, s1, 0
	ds_read_b128 v[52:55], v4 offset:4608
	ds_read_b128 v[56:59], v4 offset:4624
	ds_read_b32 v60, v4 offset:4640
	s_waitcnt vmcnt(7)
	s_waitcnt lgkmcnt(3)
	v_pk_fma_f32 v[10:11], v[72:73], v[40:41], v[10:11] op_sel_hi:[1,0,1]
	v_pk_fma_f32 v[12:13], v[72:73], v[40:41], v[12:13] op_sel:[0,1,0]
	v_pk_fma_f32 v[14:15], v[72:73], v[42:43], v[14:15] op_sel_hi:[1,0,1]
	v_pk_fma_f32 v[16:17], v[72:73], v[42:43], v[16:17] op_sel:[0,1,0]
	v_pk_fma_f32 v[18:19], v[72:73], v[44:45], v[18:19] op_sel_hi:[1,0,1]
	v_pk_fma_f32 v[20:21], v[72:73], v[44:45], v[20:21] op_sel:[0,1,0]
	v_pk_fma_f32 v[22:23], v[72:73], v[46:47], v[22:23] op_sel_hi:[1,0,1]
	v_pk_fma_f32 v[24:25], v[72:73], v[46:47], v[24:25] op_sel:[0,1,0]
	v_pk_fma_f32 v[26:27], v[72:73], v[48:49], v[26:27] op_sel_hi:[1,0,1]
	v_pk_fma_f32 v[28:29], v[74:75], v[40:41], v[28:29] op_sel_hi:[0,1,1]
	v_pk_fma_f32 v[30:31], v[74:75], v[42:43], v[30:31] op_sel_hi:[0,1,1]
	v_pk_fma_f32 v[32:33], v[74:75], v[44:45], v[32:33] op_sel_hi:[0,1,1]
	v_pk_fma_f32 v[34:35], v[74:75], v[46:47], v[34:35] op_sel_hi:[0,1,1]
	v_fmac_f32_e32 v36, v74, v48
	s_mov_b64 exec, s[14:15]
	global_load_dwordx3 v[72:74], v2, s[0:1]
	s_mov_b64 exec, -1
	s_add_u32 s0, s0, 0x180000
	s_addc_u32 s1, s1, 0
	ds_read_b128 v[40:43], v4 offset:6144
	ds_read_b128 v[44:47], v4 offset:6160
	ds_read_b32 v48, v4 offset:6176
	s_waitcnt vmcnt(7)
	s_waitcnt lgkmcnt(3)
	v_pk_fma_f32 v[10:11], v[76:77], v[52:53], v[10:11] op_sel_hi:[1,0,1]
	v_pk_fma_f32 v[12:13], v[76:77], v[52:53], v[12:13] op_sel:[0,1,0]
	v_pk_fma_f32 v[14:15], v[76:77], v[54:55], v[14:15] op_sel_hi:[1,0,1]
	v_pk_fma_f32 v[16:17], v[76:77], v[54:55], v[16:17] op_sel:[0,1,0]
	v_pk_fma_f32 v[18:19], v[76:77], v[56:57], v[18:19] op_sel_hi:[1,0,1]
	v_pk_fma_f32 v[20:21], v[76:77], v[56:57], v[20:21] op_sel:[0,1,0]
	v_pk_fma_f32 v[22:23], v[76:77], v[58:59], v[22:23] op_sel_hi:[1,0,1]
	v_pk_fma_f32 v[24:25], v[76:77], v[58:59], v[24:25] op_sel:[0,1,0]
	v_pk_fma_f32 v[26:27], v[76:77], v[60:61], v[26:27] op_sel_hi:[1,0,1]
	v_pk_fma_f32 v[28:29], v[78:79], v[52:53], v[28:29] op_sel_hi:[0,1,1]
	v_pk_fma_f32 v[30:31], v[78:79], v[54:55], v[30:31] op_sel_hi:[0,1,1]
	v_pk_fma_f32 v[32:33], v[78:79], v[56:57], v[32:33] op_sel_hi:[0,1,1]
	v_pk_fma_f32 v[34:35], v[78:79], v[58:59], v[34:35] op_sel_hi:[0,1,1]
	v_fmac_f32_e32 v36, v78, v60
	s_mov_b64 exec, s[14:15]
	global_load_dwordx3 v[76:78], v2, s[0:1]
	s_mov_b64 exec, -1
	s_add_u32 s0, s0, 0x180000
	s_addc_u32 s1, s1, 0
	ds_read_b128 v[52:55], v4 offset:7680
	ds_read_b128 v[56:59], v4 offset:7696
	ds_read_b32 v60, v4 offset:7712
	s_waitcnt vmcnt(7)
	s_waitcnt lgkmcnt(3)
	v_pk_fma_f32 v[10:11], v[80:81], v[40:41], v[10:11] op_sel_hi:[1,0,1]
	v_pk_fma_f32 v[12:13], v[80:81], v[40:41], v[12:13] op_sel:[0,1,0]
	v_pk_fma_f32 v[14:15], v[80:81], v[42:43], v[14:15] op_sel_hi:[1,0,1]
	v_pk_fma_f32 v[16:17], v[80:81], v[42:43], v[16:17] op_sel:[0,1,0]
	v_pk_fma_f32 v[18:19], v[80:81], v[44:45], v[18:19] op_sel_hi:[1,0,1]
	v_pk_fma_f32 v[20:21], v[80:81], v[44:45], v[20:21] op_sel:[0,1,0]
	v_pk_fma_f32 v[22:23], v[80:81], v[46:47], v[22:23] op_sel_hi:[1,0,1]
	v_pk_fma_f32 v[24:25], v[80:81], v[46:47], v[24:25] op_sel:[0,1,0]
	v_pk_fma_f32 v[26:27], v[80:81], v[48:49], v[26:27] op_sel_hi:[1,0,1]
	v_pk_fma_f32 v[28:29], v[82:83], v[40:41], v[28:29] op_sel_hi:[0,1,1]
	v_pk_fma_f32 v[30:31], v[82:83], v[42:43], v[30:31] op_sel_hi:[0,1,1]
	v_pk_fma_f32 v[32:33], v[82:83], v[44:45], v[32:33] op_sel_hi:[0,1,1]
	v_pk_fma_f32 v[34:35], v[82:83], v[46:47], v[34:35] op_sel_hi:[0,1,1]
	v_fmac_f32_e32 v36, v82, v48
	s_mov_b64 exec, s[14:15]
	global_load_dwordx3 v[80:82], v2, s[0:1]
	s_mov_b64 exec, -1
	s_add_u32 s0, s0, 0x180000
	s_addc_u32 s1, s1, 0
	ds_read_b128 v[40:43], v4 offset:9216
	ds_read_b128 v[44:47], v4 offset:9232
	ds_read_b32 v48, v4 offset:9248
	s_waitcnt vmcnt(7)
	s_waitcnt lgkmcnt(3)
	v_pk_fma_f32 v[10:11], v[84:85], v[52:53], v[10:11] op_sel_hi:[1,0,1]
	v_pk_fma_f32 v[12:13], v[84:85], v[52:53], v[12:13] op_sel:[0,1,0]
	v_pk_fma_f32 v[14:15], v[84:85], v[54:55], v[14:15] op_sel_hi:[1,0,1]
	v_pk_fma_f32 v[16:17], v[84:85], v[54:55], v[16:17] op_sel:[0,1,0]
	v_pk_fma_f32 v[18:19], v[84:85], v[56:57], v[18:19] op_sel_hi:[1,0,1]
	v_pk_fma_f32 v[20:21], v[84:85], v[56:57], v[20:21] op_sel:[0,1,0]
	v_pk_fma_f32 v[22:23], v[84:85], v[58:59], v[22:23] op_sel_hi:[1,0,1]
	v_pk_fma_f32 v[24:25], v[84:85], v[58:59], v[24:25] op_sel:[0,1,0]
	v_pk_fma_f32 v[26:27], v[84:85], v[60:61], v[26:27] op_sel_hi:[1,0,1]
	v_pk_fma_f32 v[28:29], v[86:87], v[52:53], v[28:29] op_sel_hi:[0,1,1]
	v_pk_fma_f32 v[30:31], v[86:87], v[54:55], v[30:31] op_sel_hi:[0,1,1]
	v_pk_fma_f32 v[32:33], v[86:87], v[56:57], v[32:33] op_sel_hi:[0,1,1]
	v_pk_fma_f32 v[34:35], v[86:87], v[58:59], v[34:35] op_sel_hi:[0,1,1]
	v_fmac_f32_e32 v36, v86, v60
	s_mov_b64 exec, s[14:15]
	global_load_dwordx3 v[84:86], v2, s[0:1]
	s_mov_b64 exec, -1
	s_add_u32 s0, s0, 0x180000
	s_addc_u32 s1, s1, 0
	ds_read_b128 v[52:55], v4 offset:10752
	ds_read_b128 v[56:59], v4 offset:10768
	ds_read_b32 v60, v4 offset:10784
	s_waitcnt vmcnt(7)
	s_waitcnt lgkmcnt(3)
	v_pk_fma_f32 v[10:11], v[88:89], v[40:41], v[10:11] op_sel_hi:[1,0,1]
	v_pk_fma_f32 v[12:13], v[88:89], v[40:41], v[12:13] op_sel:[0,1,0]
	v_pk_fma_f32 v[14:15], v[88:89], v[42:43], v[14:15] op_sel_hi:[1,0,1]
	v_pk_fma_f32 v[16:17], v[88:89], v[42:43], v[16:17] op_sel:[0,1,0]
	v_pk_fma_f32 v[18:19], v[88:89], v[44:45], v[18:19] op_sel_hi:[1,0,1]
	v_pk_fma_f32 v[20:21], v[88:89], v[44:45], v[20:21] op_sel:[0,1,0]
	v_pk_fma_f32 v[22:23], v[88:89], v[46:47], v[22:23] op_sel_hi:[1,0,1]
	v_pk_fma_f32 v[24:25], v[88:89], v[46:47], v[24:25] op_sel:[0,1,0]
	v_pk_fma_f32 v[26:27], v[88:89], v[48:49], v[26:27] op_sel_hi:[1,0,1]
	v_pk_fma_f32 v[28:29], v[90:91], v[40:41], v[28:29] op_sel_hi:[0,1,1]
	v_pk_fma_f32 v[30:31], v[90:91], v[42:43], v[30:31] op_sel_hi:[0,1,1]
	v_pk_fma_f32 v[32:33], v[90:91], v[44:45], v[32:33] op_sel_hi:[0,1,1]
	v_pk_fma_f32 v[34:35], v[90:91], v[46:47], v[34:35] op_sel_hi:[0,1,1]
	v_fmac_f32_e32 v36, v90, v48
	s_mov_b64 exec, s[14:15]
	global_load_dwordx3 v[88:90], v2, s[0:1]
	s_mov_b64 exec, -1
	s_add_u32 s0, s0, 0x180000
	s_addc_u32 s1, s1, 0
	ds_read_b128 v[40:43], v4 offset:12288
	ds_read_b128 v[44:47], v4 offset:12304
	ds_read_b32 v48, v4 offset:12320
	s_waitcnt vmcnt(7)
	s_waitcnt lgkmcnt(3)
	v_pk_fma_f32 v[10:11], v[92:93], v[52:53], v[10:11] op_sel_hi:[1,0,1]
	v_pk_fma_f32 v[12:13], v[92:93], v[52:53], v[12:13] op_sel:[0,1,0]
	v_pk_fma_f32 v[14:15], v[92:93], v[54:55], v[14:15] op_sel_hi:[1,0,1]
	v_pk_fma_f32 v[16:17], v[92:93], v[54:55], v[16:17] op_sel:[0,1,0]
	v_pk_fma_f32 v[18:19], v[92:93], v[56:57], v[18:19] op_sel_hi:[1,0,1]
	v_pk_fma_f32 v[20:21], v[92:93], v[56:57], v[20:21] op_sel:[0,1,0]
	v_pk_fma_f32 v[22:23], v[92:93], v[58:59], v[22:23] op_sel_hi:[1,0,1]
	v_pk_fma_f32 v[24:25], v[92:93], v[58:59], v[24:25] op_sel:[0,1,0]
	v_pk_fma_f32 v[26:27], v[92:93], v[60:61], v[26:27] op_sel_hi:[1,0,1]
	v_pk_fma_f32 v[28:29], v[94:95], v[52:53], v[28:29] op_sel_hi:[0,1,1]
	v_pk_fma_f32 v[30:31], v[94:95], v[54:55], v[30:31] op_sel_hi:[0,1,1]
	v_pk_fma_f32 v[32:33], v[94:95], v[56:57], v[32:33] op_sel_hi:[0,1,1]
	v_pk_fma_f32 v[34:35], v[94:95], v[58:59], v[34:35] op_sel_hi:[0,1,1]
	v_fmac_f32_e32 v36, v94, v60
	s_mov_b64 exec, s[14:15]
	global_load_dwordx3 v[92:94], v2, s[0:1]
	s_mov_b64 exec, -1
	s_add_u32 s0, s0, 0x180000
	s_addc_u32 s1, s1, 0
	ds_read_b128 v[52:55], v4 offset:13824
	ds_read_b128 v[56:59], v4 offset:13840
	ds_read_b32 v60, v4 offset:13856
	v_add_u32_e32 v4, 0x3000, v4
	s_add_u32 s16, s16, 1
	s_cmp_lt_u32 s16, 8
	s_cbranch_scc1 .Lgv_loop
	s_waitcnt vmcnt(0) lgkmcnt(0)
	v_add_u32_e32 v7, s4, v5
	v_mul_u32_u24_e32 v7, 0x6c0, v7
	v_lshl_add_u32 v7, v6, 2, v7
	v_add_u32_e32 v7, 0x18000, v7
	ds_write_b32 v7, v10
	ds_write_b32 v7, v11 offset:64
	ds_write_b32 v7, v12 offset:128
	ds_write_b32 v7, v13 offset:192
	ds_write_b32 v7, v14 offset:256
	ds_write_b32 v7, v15 offset:320
	ds_write_b32 v7, v16 offset:384
	ds_write_b32 v7, v17 offset:448
	ds_write_b32 v7, v18 offset:512
	ds_write_b32 v7, v19 offset:576
	ds_write_b32 v7, v20 offset:640
	ds_write_b32 v7, v21 offset:704
	ds_write_b32 v7, v22 offset:768
	ds_write_b32 v7, v23 offset:832
	ds_write_b32 v7, v24 offset:896
	ds_write_b32 v7, v25 offset:960
	ds_write_b32 v7, v26 offset:1024
	ds_write_b32 v7, v27 offset:1088
	ds_write_b32 v7, v28 offset:1152
	ds_write_b32 v7, v29 offset:1216
	ds_write_b32 v7, v30 offset:1280
	ds_write_b32 v7, v31 offset:1344
	ds_write_b32 v7, v32 offset:1408
	ds_write_b32 v7, v33 offset:1472
	ds_write_b32 v7, v34 offset:1536
	ds_write_b32 v7, v35 offset:1600
	ds_write_b32 v7, v36 offset:1664
	s_waitcnt lgkmcnt(0)
	s_barrier
	v_cmp_gt_u32_e32 vcc, 0x1b0, v0
	s_and_saveexec_b64 s[8:9], vcc
	s_cbranch_execz .Lgv_fin_done
	v_lshlrev_b32_e32 v8, 2, v0
	v_add_u32_e32 v8, 0x18000, v8
	ds_read_b32 v100, v8
	ds_read_b32 v101, v8 offset:1728
	ds_read_b32 v102, v8 offset:3456
	ds_read_b32 v103, v8 offset:5184
	ds_read_b32 v104, v8 offset:6912
	ds_read_b32 v105, v8 offset:8640
	ds_read_b32 v106, v8 offset:10368
	ds_read_b32 v107, v8 offset:12096
	ds_read_b32 v108, v8 offset:13824
	ds_read_b32 v109, v8 offset:15552
	ds_read_b32 v110, v8 offset:17280
	ds_read_b32 v111, v8 offset:19008
	ds_read_b32 v112, v8 offset:20736
	ds_read_b32 v113, v8 offset:22464
	ds_read_b32 v114, v8 offset:24192
	ds_read_b32 v115, v8 offset:25920
	ds_read_b32 v116, v8 offset:27648
	ds_read_b32 v117, v8 offset:29376
	ds_read_b32 v118, v8 offset:31104
	ds_read_b32 v119, v8 offset:32832
	ds_read_b32 v120, v8 offset:34560
	ds_read_b32 v121, v8 offset:36288
	ds_read_b32 v122, v8 offset:38016
	ds_read_b32 v123, v8 offset:39744
	ds_read_b32 v124, v8 offset:41472
	ds_read_b32 v125, v8 offset:43200
	ds_read_b32 v126, v8 offset:44928
	ds_read_b32 v127, v8 offset:46656
	ds_read_b32 v128, v8 offset:48384
	ds_read_b32 v129, v8 offset:50112
	ds_read_b32 v130, v8 offset:51840
	ds_read_b32 v131, v8 offset:53568
	v_lshrrev_b32_e32 v9, 4, v0
	v_and_b32_e32 v132, 15, v0
	v_lshrrev_b32_e32 v133, 1, v9
	v_subrev_u32_e32 v134, 18, v9
	v_and_b32_e32 v136, 1, v9
	v_mov_b32_e32 v137, 2
	v_cmp_gt_u32_e32 vcc, 18, v9
	s_nop 1
	v_cndmask_b32_e32 v133, v134, v133, vcc
	v_cndmask_b32_e32 v136, v137, v136, vcc
	v_mul_u32_u24_e32 v132, 3, v132
	v_add_u32_e32 v132, v132, v136
	s_mul_i32 s10, s30, 48
	v_add_u32_e32 v132, s10, v132
	v_mul_u32_u24_e32 v133, 0x3000, v133
	v_add_u32_e32 v133, v133, v132
	v_lshlrev_b32_e32 v133, 2, v133
	v_lshlrev_b32_e32 v132, 2, v132
	v_readlane_b32 s14, v254, 12
	v_readlane_b32 s15, v254, 13
	s_add_u32 s16, s74, 0x100000
	s_addc_u32 s17, s75, 0
	s_nop 4
	global_load_dword v12, v132, s[14:15]
	s_waitcnt vmcnt(0) lgkmcnt(0)
	v_add_f32_e32 v12, v12, v100
	v_add_f32_e32 v12, v12, v101
	v_add_f32_e32 v12, v12, v102
	v_add_f32_e32 v12, v12, v103
	v_add_f32_e32 v12, v12, v104
	v_add_f32_e32 v12, v12, v105
	v_add_f32_e32 v12, v12, v106
	v_add_f32_e32 v12, v12, v107
	v_add_f32_e32 v12, v12, v108
	v_add_f32_e32 v12, v12, v109
	v_add_f32_e32 v12, v12, v110
	v_add_f32_e32 v12, v12, v111
	v_add_f32_e32 v12, v12, v112
	v_add_f32_e32 v12, v12, v113
	v_add_f32_e32 v12, v12, v114
	v_add_f32_e32 v12, v12, v115
	v_add_f32_e32 v12, v12, v116
	v_add_f32_e32 v12, v12, v117
	v_add_f32_e32 v12, v12, v118
	v_add_f32_e32 v12, v12, v119
	v_add_f32_e32 v12, v12, v120
	v_add_f32_e32 v12, v12, v121
	v_add_f32_e32 v12, v12, v122
	v_add_f32_e32 v12, v12, v123
	v_add_f32_e32 v12, v12, v124
	v_add_f32_e32 v12, v12, v125
	v_add_f32_e32 v12, v12, v126
	v_add_f32_e32 v12, v12, v127
	v_add_f32_e32 v12, v12, v128
	v_add_f32_e32 v12, v12, v129
	v_add_f32_e32 v12, v12, v130
	v_add_f32_e32 v12, v12, v131
	global_store_dword v133, v12, s[16:17]
.Lgv_fin_done:
	s_or_b64 exec, exec, s[8:9]
	s_branch .LBB0_20
.Lgv_old:
	s_cmpk_gt_i32 s92, 0xbf
	s_cbranch_scc1 .LBB0_20
	v_lshlrev_b32_e32 v2, 2, v0
	v_or_b32_e32 v4, 0x1000, v2
	v_mov_b32_e32 v5, v3
	v_lshl_add_u64 v[96:97], s[64:65], 0, v[4:5]
	v_lshl_add_u64 v[98:99], s[56:57], 0, v[4:5]
	v_mbcnt_lo_u32_b32 v4, -1, 0
	v_mbcnt_hi_u32_b32 v4, -1, v4
	v_and_b32_e32 v7, 64, v4
	v_xor_b32_e32 v5, 16, v4
	v_add_u32_e32 v7, 64, v7
	v_cmp_lt_i32_e32 vcc, v5, v7
	v_lshrrev_b32_e32 v8, 4, v0
	v_and_b32_e32 v6, 15, v0
	v_cndmask_b32_e32 v5, v4, v5, vcc
	v_lshlrev_b32_e32 v183, 2, v5
	v_xor_b32_e32 v5, 32, v4
	v_cmp_lt_i32_e32 vcc, v5, v7
	v_lshl_add_u64 v[68:69], s[56:57], 0, v[2:3]
	s_mov_b64 s[12:13], 0x8000
	s_mov_b64 s[18:19], 0x2800
	v_cndmask_b32_e32 v4, v4, v5, vcc
	v_lshl_add_u64 v[76:77], v[68:69], 0, s[12:13]
	v_lshl_add_u64 v[82:83], v[68:69], 0, s[18:19]
	s_mov_b64 s[18:19], 0x4800
	v_lshl_add_u64 v[106:107], v[98:99], 0, s[12:13]
	v_lshlrev_b32_e32 v6, 4, v6
	s_add_i32 s13, 0, 0x12000
	v_lshlrev_b32_e32 v196, 2, v4
	v_lshrrev_b32_e32 v4, 6, v0
	v_mul_u32_u24_e32 v7, 0xc000, v8
	v_readlane_b32 s36, v254, 0
	s_mov_b64 s[6:7], 0x2000
	v_lshl_add_u64 v[84:85], v[68:69], 0, s[18:19]
	s_mov_b64 s[18:19], 0x6800
	v_add_u32_e32 v9, s13, v6
	v_mul_hi_u32_u24_e32 v5, 0xc000, v4
	v_mul_u32_u24_e32 v4, 0xc000, v4
	v_or_b32_e32 v6, v7, v6
	v_mul_hi_u32_u24_e32 v7, 0xc000, v8
	v_readlane_b32 s46, v254, 10
	v_readlane_b32 s47, v254, 11
	v_lshl_add_u64 v[70:71], v[68:69], 0, s[6:7]
	v_lshl_add_u64 v[86:87], v[68:69], 0, s[18:19]
	s_mov_b64 s[18:19], 0x8800
	v_lshl_add_u64 v[100:101], v[98:99], 0, s[6:7]
	v_lshl_or_b32 v4, v1, 2, v4
	v_lshl_add_u64 v[6:7], s[46:47], 0, v[6:7]
	s_mov_b64 s[6:7], 0xc00000
	v_lshl_add_u64 v[88:89], v[68:69], 0, s[18:19]
	s_mov_b64 s[18:19], 0xa800
	v_lshl_add_u64 v[112:113], v[6:7], 0, s[6:7]
	v_lshl_add_u64 v[4:5], s[74:75], 0, v[4:5]
	s_mov_b64 s[6:7], 0x100000
	s_movk_i32 s0, 0x240
	s_mov_b64 s[8:9], 0x4000
	s_mov_b64 s[10:11], 0x6000
	s_mov_b64 s[14:15], 0xa000
	v_lshl_add_u64 v[90:91], v[68:69], 0, s[18:19]
	s_mov_b64 s[18:19], 0xc800
	v_lshl_add_u64 v[114:115], v[4:5], 0, s[6:7]
	s_movk_i32 s6, 0x700
	v_cmp_gt_u32_e64 s[4:5], s0, v0
	v_lshl_add_u64 v[66:67], s[64:65], 0, v[2:3]
	v_lshl_add_u64 v[72:73], v[68:69], 0, s[8:9]
	v_lshl_add_u64 v[74:75], v[68:69], 0, s[10:11]
	v_lshl_add_u64 v[78:79], v[68:69], 0, s[14:15]
	s_mov_b64 s[16:17], 0xc000
	s_mov_b64 s[0:1], 0xe000
	v_lshl_add_u64 v[92:93], v[68:69], 0, s[18:19]
	s_mov_b64 s[18:19], 0xe800
	v_lshl_add_u64 v[102:103], v[98:99], 0, s[8:9]
	v_lshl_add_u64 v[104:105], v[98:99], 0, s[10:11]
	v_lshl_add_u64 v[108:109], v[98:99], 0, s[14:15]
	s_mov_b64 s[8:9], 0x1800
	s_mov_b64 s[10:11], 0x3800
	s_mov_b64 s[64:65], 0x5800
	s_mov_b64 s[78:79], 0x7800
	s_mov_b64 s[80:81], 0x9800
	s_mov_b64 s[82:83], 0xb800
	s_mov_b64 s[84:85], 0xd800
	s_mov_b64 s[86:87], 0xf800
	v_mul_u32_u24_e32 v3, 36, v0
	s_mul_i32 s14, s91, 0x900
	v_and_or_b32 v2, v2, s6, v181
	v_cmp_gt_u32_e64 s[2:3], 16, v1
	v_lshl_add_u64 v[80:81], v[68:69], 0, s[16:17]
	v_lshl_add_u64 v[94:95], v[68:69], 0, s[18:19]
	v_lshl_add_u64 v[110:111], v[98:99], 0, s[16:17]
	s_lshl_b32 s12, s92, 6
	s_lshl_b32 s18, s33, 6
	v_mad_u32_u24 v197, v8, 36, 0
	v_add_u32_e32 v198, s13, v2
	s_mov_b64 s[6:7], 0
	v_add_u32_e32 v199, 0, v3
	s_mov_b32 s19, 0xff400000
	s_mov_b32 s20, 0xff580000
	s_mov_b32 s21, 0xff700000
	s_mov_b32 s22, 0xff880000
	s_mov_b32 s23, 0xffa00000
	v_lshl_add_u64 v[116:117], v[68:69], 0, s[0:1]
	s_mov_b32 s24, 0xffb80000
	v_lshl_add_u64 v[118:119], v[98:99], 0, s[0:1]
	s_mov_b32 s25, 0xffd00000
	s_mov_b32 s26, 0xffe80000
	s_mov_b32 s27, 0x180000
	s_mov_b32 s28, 0x300000
	v_lshl_add_u64 v[120:121], v[66:67], 0, s[8:9]
	s_mov_b32 s29, 0x480000
	s_mov_b32 s31, 0x600000
	v_lshl_add_u64 v[122:123], v[68:69], 0, s[8:9]
	s_mov_b32 s46, 0x780000
	s_mov_b32 s47, 0x900000
	s_mov_b32 s56, 0xa80000
	v_add_u32_e32 v200, s14, v9
	s_mov_b64 s[14:15], 0x1800000
	v_lshl_add_u64 v[124:125], v[68:69], 0, s[10:11]
	s_mov_b64 s[16:17], 0x60000
	s_mov_b32 s57, s92
	v_or_b32_e32 v201, 0xfffffe00, v0
	v_lshl_add_u64 v[126:127], v[68:69], 0, s[64:65]
	v_lshl_add_u64 v[128:129], v[68:69], 0, s[78:79]
	v_lshl_add_u64 v[130:131], v[68:69], 0, s[80:81]
	v_lshl_add_u64 v[132:133], v[68:69], 0, s[82:83]
	v_lshl_add_u64 v[134:135], v[68:69], 0, s[84:85]
	v_lshl_add_u64 v[136:137], v[68:69], 0, s[86:87]
	v_readlane_b32 s37, v254, 1
	v_readlane_b32 s38, v254, 2
	v_readlane_b32 s39, v254, 3
	v_readlane_b32 s40, v254, 4
	v_readlane_b32 s41, v254, 5
	v_readlane_b32 s42, v254, 6
	v_readlane_b32 s43, v254, 7
	v_readlane_b32 s44, v254, 8
	v_readlane_b32 s45, v254, 9
	v_readlane_b32 s48, v254, 12
	v_readlane_b32 s49, v254, 13
	v_readlane_b32 s50, v254, 14
	v_readlane_b32 s51, v254, 15
	s_branch .LBB0_11
